# code placement: K-loop head aligned to 64 bytes
# speedup vs baseline: 1.0021x; 1.0021x over previous
; #define PG8_LDA(dst, b, h) do { _Pragma("unroll") for (int m = 0; m < 4; ++m) _Pragma("unroll") for (int k = 0; k < 2; ++k) dst[m][k] = *(const LAS bf16x8*)(lds + PG8_SA(b, h) + aoff + m * 2048 + k * 1024); } while (0)
; #define PG8_LDB(dst, b, h) do { _Pragma("unroll") for (int n = 0; n < 2; ++n) _Pragma("unroll") for (int k = 0; k < 2; ++k) dst[n][k] = *(const LAS bf16x8*)(lds + PG8_SB(b, h) + boff + n * 2048 + k * 1024); } while (0)
; #define PG8_SCHED __builtin_amdgcn_sched_barrier(0)
; #define PG8_STA(bufoff, gbase, ld) PG8_STAGE(bufoff, gbase, RA0 * (unsigned)(ld) + CC0, RA1 * (unsigned)(ld) + CC1)
; __device__ __forceinline__ void gemm_phase(LAS unsigned char* lds, const Sched& S, const Epi& E) {
;     ...
;         const char* nA = has_next ? nxt.a : cA; const char* nB = has_next ? nxt.b : cB;
;         const int nlda = has_next ? nxt.lda : lda, nldb = has_next ? nxt.ldb : ldb;
;         const size_t hA = (size_t)HALF * lda * 2;
;         const int nt = cur.nt;
;         const int nt_main = has_next ? nt : nt - 2;
;         for (int t = 0; t < nt_main; t += 2) {
;             const bool last = (t == nt - 2);
;             const char* a1 = cA + (size_t)(t + 1) * kstep;
;             const char* a2 = last ? nA : cA + (size_t)(t + 2) * kstep; const char* b2 = last ? nB : cB + (size_t)(t + 2) * kstep;
;             const char* a3 = a2 + kstep; const char* b3 = b2 + kstep;
;             const int xlda = last ? nlda : lda, xldb = last ? nldb : ldb;
;             const size_t xhA = (size_t)HALF * xlda * 2, xhB = (size_t)HALF * xldb * 2;
;             PG8_LDB(B0, 0, 0); PG8_LDB(B1, 0, 1); PG8_SCHED; PG8_LDA(At, 0, 0); PG8_STA(PG8_SA(1, 1), a1 + hA, lda);
;     ...
; #pragma unroll
;         for (int a = 0; a < 2; ++a)
; #pragma unroll
;             for (int b = 0; b < 2; ++b)
; #pragma unroll
;                 for (int m = 0; m < 4; ++m)
; #pragma unroll
;                     for (int n = 0; n < 2; ++n) acc[a][b][m][n] = (f32x4){0.f, 0.f, 0.f, 0.f};
.LBB0_261:
	s_mov_b32 s21, s31
	s_lshl_b64 s[66:67], s[20:21], 8
	s_add_i32 s21, s60, -2
	s_and_b64 s[26:27], s[42:43], exec
	s_cselect_b32 s68, s60, s21
	s_cmp_lt_i32 s68, 1
	s_cbranch_scc1 .LBB0_274
	s_add_u32 vcc_lo, s96, 0x80
	s_addc_u32 vcc_hi, s97, 0
	s_add_u32 s2, s8, 0x100
	s_addc_u32 s72, s9, 0
	v_mad_u64_u32 v[2:3], s[8:9], s20, v235, v[206:207]
	v_mov_b32_e32 v3, v1
	s_waitcnt lgkmcnt(0)
	v_lshl_add_u64 v[130:131], s[66:67], 0, v[2:3]
	v_mad_u64_u32 v[2:3], s[8:9], s20, v236, v[208:209]
	v_mov_b32_e32 v3, v1
	v_lshl_add_u64 v[132:133], s[66:67], 0, v[2:3]
	s_mov_b32 s3, s92
	s_mov_b32 s8, 0
	v_mov_b64_e32 v[2:3], 0
	v_mov_b64_e32 v[4:5], 0
	v_mov_b64_e32 v[6:7], 0
	v_mov_b64_e32 v[8:9], 0
	v_mov_b64_e32 v[10:11], 0
	v_mov_b64_e32 v[12:13], 0
	v_mov_b64_e32 v[14:15], 0
	v_mov_b64_e32 v[16:17], 0
	v_mov_b64_e32 v[18:19], 0
	v_mov_b64_e32 v[20:21], 0
	v_mov_b64_e32 v[22:23], 0
	v_mov_b64_e32 v[24:25], 0
	v_mov_b64_e32 v[26:27], 0
	v_mov_b64_e32 v[28:29], 0
	v_mov_b64_e32 v[30:31], 0
	v_mov_b64_e32 v[32:33], 0
	v_mov_b64_e32 v[34:35], 0
	v_mov_b64_e32 v[36:37], 0
	v_mov_b64_e32 v[38:39], 0
	v_mov_b64_e32 v[40:41], 0
	v_mov_b64_e32 v[42:43], 0
	v_mov_b64_e32 v[44:45], 0
	v_mov_b64_e32 v[46:47], 0
	v_mov_b64_e32 v[48:49], 0
	v_mov_b64_e32 v[50:51], 0
	v_mov_b64_e32 v[52:53], 0
	v_mov_b64_e32 v[54:55], 0
	v_mov_b64_e32 v[56:57], 0
	v_mov_b64_e32 v[58:59], 0
	v_mov_b64_e32 v[60:61], 0
	v_mov_b64_e32 v[62:63], 0
	v_mov_b64_e32 v[64:65], 0
	v_mov_b64_e32 v[66:67], 0
	v_mov_b64_e32 v[68:69], 0
	v_mov_b64_e32 v[70:71], 0
	v_mov_b64_e32 v[72:73], 0
	v_mov_b64_e32 v[74:75], 0
	v_mov_b64_e32 v[76:77], 0
	v_mov_b64_e32 v[78:79], 0
	v_mov_b64_e32 v[80:81], 0
	v_mov_b64_e32 v[82:83], 0
	v_mov_b64_e32 v[84:85], 0
	v_mov_b64_e32 v[86:87], 0
	v_mov_b64_e32 v[88:89], 0
	v_mov_b64_e32 v[90:91], 0
	v_mov_b64_e32 v[92:93], 0
	v_mov_b64_e32 v[94:95], 0
	v_mov_b64_e32 v[96:97], 0
	v_mov_b64_e32 v[98:99], 0
	v_mov_b64_e32 v[100:101], 0
	v_mov_b64_e32 v[102:103], 0
	v_mov_b64_e32 v[104:105], 0
	v_mov_b64_e32 v[106:107], 0
	v_mov_b64_e32 v[108:109], 0
	v_mov_b64_e32 v[110:111], 0
	v_mov_b64_e32 v[112:113], 0
	v_mov_b64_e32 v[114:115], 0
	v_mov_b64_e32 v[116:117], 0
	v_mov_b64_e32 v[118:119], 0
	v_mov_b64_e32 v[120:121], 0
	v_mov_b64_e32 v[122:123], 0
	v_mov_b64_e32 v[124:125], 0
	v_mov_b64_e32 v[126:127], 0
	v_mov_b64_e32 v[128:129], 0
	.p2align 6
